# v26 + row sums via v_dot2c_f32_bf16 with four independent accumulators (no dependent DLop chain) replacing the ones-MFMAs
# baseline (speedup 1.0000x reference)
.LBB0_738:
	v_cvt_pk_bf16_f32 v50, v50, v51
	v_cvt_pk_bf16_f32 v51, v52, v53
	v_cvt_pk_bf16_f32 v52, v54, v182
	v_cvt_pk_bf16_f32 v53, v56, v183
	v_cvt_pk_bf16_f32 v54, v55, v57
	v_cvt_pk_bf16_f32 v55, v58, v59
	v_mov_b32_e32 v82, 0
	v_mov_b32_e32 v83, 0
	v_mov_b32_e32 v84, 0
	v_mov_b32_e32 v85, 0
	v_dot2c_f32_bf16_e32 v82, v50, v198
	v_dot2c_f32_bf16_e32 v83, v51, v198
	v_dot2c_f32_bf16_e32 v84, v52, v198
	v_dot2c_f32_bf16_e32 v85, v53, v198
	v_cvt_pk_bf16_f32 v56, v60, v61
	v_cvt_pk_bf16_f32 v57, v62, v63
	v_mfma_f32_32x32x16_bf16 v[2:17], v[170:173], v[50:53], v[2:17]
	ds_read_b64_tr_b16 v[58:59], v221 offset:28672
	ds_read_b64_tr_b16 v[60:61], v221 offset:29184
	v_exp_f32_e32 v62, v34
	v_exp_f32_e32 v63, v35
	v_exp_f32_e32 v64, v36
	v_exp_f32_e32 v65, v37
	v_mfma_f32_32x32x16_bf16 v[18:33], v[166:169], v[50:53], v[18:33]
	ds_read_b64_tr_b16 v[34:35], v221 offset:32768
	ds_read_b64_tr_b16 v[36:37], v221 offset:33280
	v_exp_f32_e32 v50, v38
	v_exp_f32_e32 v51, v39
	v_exp_f32_e32 v52, v40
	v_exp_f32_e32 v41, v41
	v_dot2c_f32_bf16_e32 v82, v54, v198
	v_dot2c_f32_bf16_e32 v83, v55, v198
	v_dot2c_f32_bf16_e32 v84, v56, v198
	v_dot2c_f32_bf16_e32 v85, v57, v198
	v_cvt_pk_bf16_f32 v38, v62, v63
	v_cvt_pk_bf16_f32 v39, v64, v65
	v_cvt_pk_bf16_f32 v40, v50, v51
	v_cvt_pk_bf16_f32 v41, v52, v41
	s_waitcnt lgkmcnt(6)
	v_mfma_f32_32x32x16_bf16 v[2:17], v[178:181], v[54:57], v[2:17]
	ds_read_b64_tr_b16 v[50:51], v221 offset:29696
	ds_read_b64_tr_b16 v[52:53], v221 offset:30208
	v_exp_f32_e32 v62, v42
	v_exp_f32_e32 v63, v43
	v_exp_f32_e32 v64, v44
	v_exp_f32_e32 v65, v45
	s_waitcnt lgkmcnt(6)
	v_mfma_f32_32x32x16_bf16 v[18:33], v[174:177], v[54:57], v[18:33]
	ds_read_b64_tr_b16 v[42:43], v221 offset:33792
	ds_read_b64_tr_b16 v[44:45], v221 offset:34304
	v_exp_f32_e32 v54, v46
	v_exp_f32_e32 v55, v47
	v_exp_f32_e32 v56, v48
	v_exp_f32_e32 v49, v49
	v_dot2c_f32_bf16_e32 v82, v38, v198
	v_dot2c_f32_bf16_e32 v83, v39, v198
	v_dot2c_f32_bf16_e32 v84, v40, v198
	v_dot2c_f32_bf16_e32 v85, v41, v198
	v_cvt_pk_bf16_f32 v46, v62, v63
	v_cvt_pk_bf16_f32 v47, v64, v65
	v_cvt_pk_bf16_f32 v48, v54, v55
	v_cvt_pk_bf16_f32 v49, v56, v49
	s_and_saveexec_b64 s[0:1], s[44:45]
	s_cbranch_execz .LBB0_740
	s_waitcnt vmcnt(2)
	ds_write_b128 v195, v[162:165]

.LBB0_742:
	s_or_b64 exec, exec, s[0:1]
	s_waitcnt lgkmcnt(5)
	v_mfma_f32_32x32x16_bf16 v[18:33], v[34:37], v[38:41], v[18:33]
	v_dot2c_f32_bf16_e32 v82, v46, v198
	v_dot2c_f32_bf16_e32 v83, v47, v198
	v_dot2c_f32_bf16_e32 v84, v48, v198
	v_dot2c_f32_bf16_e32 v85, v49, v198
	s_nop 2
	v_add_f32_e32 v82, v82, v83
	v_add_f32_e32 v84, v84, v85
	v_add_f32_e32 v82, v82, v84
	v_mov_b32_e32 v83, v82
	s_nop 1
	v_permlane32_swap_b32_e32 v82, v83
	v_add_f32_e32 v82, v82, v83
	s_waitcnt vmcnt(0)
	ds_write_b128 v217, v[154:157] offset:34816
	s_waitcnt lgkmcnt(4)
	v_mfma_f32_32x32x16_bf16 v[2:17], v[50:53], v[46:49], v[2:17]
	s_waitcnt lgkmcnt(2)
	v_mfma_f32_32x32x16_bf16 v[18:33], v[42:45], v[46:49], v[18:33]
	s_and_b64 vcc, exec, s[14:15]
	s_waitcnt lgkmcnt(0)
	s_barrier
	s_cbranch_vccz .LBB0_744
	v_sub_f32_e32 v113, v113, v190
	v_sub_f32_e32 v112, v112, v190
	v_sub_f32_e32 v111, v111, v190
	v_sub_f32_e32 v110, v110, v190
	v_sub_f32_e32 v109, v109, v190
	v_sub_f32_e32 v108, v108, v190
	v_sub_f32_e32 v107, v107, v190
	v_sub_f32_e32 v106, v106, v190
	v_sub_f32_e32 v105, v105, v190
	v_sub_f32_e32 v104, v104, v190
	v_sub_f32_e32 v103, v103, v190
	v_sub_f32_e32 v102, v102, v190
	v_sub_f32_e32 v101, v101, v190
	v_sub_f32_e32 v100, v100, v190
	v_sub_f32_e32 v99, v99, v190
	v_sub_f32_e32 v98, v98, v190
	v_sub_f32_e32 v81, v81, v190
	v_sub_f32_e32 v80, v80, v190
	v_sub_f32_e32 v79, v79, v190
	v_sub_f32_e32 v78, v78, v190
	v_sub_f32_e32 v77, v77, v190
	v_sub_f32_e32 v76, v76, v190
	v_sub_f32_e32 v75, v75, v190
	v_sub_f32_e32 v74, v74, v190
	v_sub_f32_e32 v73, v73, v190
	v_sub_f32_e32 v72, v72, v190
	v_sub_f32_e32 v71, v71, v190
	v_sub_f32_e32 v70, v70, v190
	v_sub_f32_e32 v69, v69, v190
	v_sub_f32_e32 v68, v68, v190
	v_sub_f32_e32 v67, v67, v190
	v_sub_f32_e32 v66, v66, v190

.LBB0_749:
	v_cvt_pk_bf16_f32 v108, v96, v97
	v_cvt_pk_bf16_f32 v109, v98, v99
	v_cvt_pk_bf16_f32 v110, v100, v102
	v_cvt_pk_bf16_f32 v111, v103, v186
	v_cvt_pk_bf16_f32 v102, v84, v85
	v_cvt_pk_bf16_f32 v103, v86, v87
	v_mov_b32_e32 v84, 0
	v_mov_b32_e32 v85, 0
	v_mov_b32_e32 v86, 0
	v_mov_b32_e32 v87, 0
	v_dot2c_f32_bf16_e32 v84, v108, v198
	v_dot2c_f32_bf16_e32 v85, v109, v198
	v_dot2c_f32_bf16_e32 v86, v110, v198
	v_dot2c_f32_bf16_e32 v87, v111, v198
	v_cvt_pk_bf16_f32 v100, v101, v104
	v_cvt_pk_bf16_f32 v101, v105, v106
	v_mfma_f32_32x32x16_bf16 v[2:17], v[170:173], v[108:111], v[2:17]
	ds_read_b64_tr_b16 v[104:105], v221 offset:36864
	ds_read_b64_tr_b16 v[106:107], v221 offset:37376
	v_exp_f32_e32 v112, v66
	v_exp_f32_e32 v113, v67
	v_exp_f32_e32 v170, v68
	v_exp_f32_e32 v171, v69
	v_mfma_f32_32x32x16_bf16 v[18:33], v[166:169], v[108:111], v[18:33]
	ds_read_b64_tr_b16 v[66:67], v221 offset:40960
	ds_read_b64_tr_b16 v[68:69], v221 offset:41472
	v_exp_f32_e32 v108, v70
	v_exp_f32_e32 v109, v71
	v_exp_f32_e32 v110, v72
	v_exp_f32_e32 v73, v73
	v_dot2c_f32_bf16_e32 v84, v100, v198
	v_dot2c_f32_bf16_e32 v85, v101, v198
	v_dot2c_f32_bf16_e32 v86, v102, v198
	v_dot2c_f32_bf16_e32 v87, v103, v198
	v_cvt_pk_bf16_f32 v70, v112, v113
	v_cvt_pk_bf16_f32 v71, v170, v171
	v_cvt_pk_bf16_f32 v72, v108, v109
	v_cvt_pk_bf16_f32 v73, v110, v73
	s_waitcnt lgkmcnt(6)
	v_mfma_f32_32x32x16_bf16 v[2:17], v[178:181], v[100:103], v[2:17]
	ds_read_b64_tr_b16 v[108:109], v221 offset:37888
	ds_read_b64_tr_b16 v[110:111], v221 offset:38400
	v_exp_f32_e32 v112, v74
	v_exp_f32_e32 v113, v75
	v_exp_f32_e32 v166, v76
	v_exp_f32_e32 v167, v77
	s_waitcnt lgkmcnt(6)
	v_mfma_f32_32x32x16_bf16 v[18:33], v[174:177], v[100:103], v[18:33]
	ds_read_b64_tr_b16 v[74:75], v221 offset:41984
	ds_read_b64_tr_b16 v[76:77], v221 offset:42496
	v_exp_f32_e32 v100, v78
	v_exp_f32_e32 v101, v79
	v_exp_f32_e32 v102, v80
	v_exp_f32_e32 v81, v81
	v_dot2c_f32_bf16_e32 v84, v70, v198
	v_dot2c_f32_bf16_e32 v85, v71, v198
	v_dot2c_f32_bf16_e32 v86, v72, v198
	v_dot2c_f32_bf16_e32 v87, v73, v198
	v_cvt_pk_bf16_f32 v78, v112, v113
	v_cvt_pk_bf16_f32 v79, v166, v167
	v_cvt_pk_bf16_f32 v80, v100, v101
	v_cvt_pk_bf16_f32 v81, v102, v81
	s_and_saveexec_b64 s[0:1], s[44:45]
	s_cbranch_execz .LBB0_751
	s_waitcnt vmcnt(2)
	ds_write_b128 v195, v[162:165] offset:13312

.LBB0_753:
	s_or_b64 exec, exec, s[0:1]
	s_waitcnt lgkmcnt(5)
	v_mfma_f32_32x32x16_bf16 v[18:33], v[66:69], v[70:73], v[18:33]
	v_dot2c_f32_bf16_e32 v84, v78, v198
	v_dot2c_f32_bf16_e32 v85, v79, v198
	v_dot2c_f32_bf16_e32 v86, v80, v198
	v_dot2c_f32_bf16_e32 v87, v81, v198
	s_nop 2
	v_add_f32_e32 v84, v84, v85
	v_add_f32_e32 v86, v86, v87
	v_add_f32_e32 v84, v84, v86
	v_mov_b32_e32 v85, v84
	s_nop 1
	v_permlane32_swap_b32_e32 v84, v85
	v_add_f32_e32 v84, v84, v85
	s_waitcnt vmcnt(0)
	ds_write_b128 v217, v[154:157] offset:26624
	s_waitcnt lgkmcnt(4)
	v_mfma_f32_32x32x16_bf16 v[2:17], v[108:111], v[78:81], v[2:17]
	s_waitcnt lgkmcnt(2)
	v_mfma_f32_32x32x16_bf16 v[18:33], v[74:77], v[78:81], v[18:33]
	v_fmac_f32_e32 v82, v222, v0
	s_mov_b64 s[0:1], 0x80000
	v_cndmask_b32_e64 v191, v223, v83, s[48:49]
	s_cmp_lt_u32 s16, 30
	v_lshl_add_u64 v[214:215], v[214:215], 0, s[0:1]
	s_nop 1
	v_fmac_f32_e32 v84, v82, v218
	s_waitcnt lgkmcnt(0)
	s_barrier
	s_cbranch_scc0 .LBB0_714
	v_mov_b32_e32 v222, v84
	s_andn2_b64 vcc, exec, s[14:15]
	s_cbranch_vccz .LBB0_732
	s_branch .LBB0_733

.LBB0_830:
	v_fmac_f32_e32 v50, v34, v0
	v_cvt_pk_bf16_f32 v118, v35, v48
	v_cvt_pk_bf16_f32 v119, v49, v128
	v_cvt_pk_bf16_f32 v120, v44, v45
	v_cvt_pk_bf16_f32 v121, v46, v47
	s_mov_b32 s38, s36
	s_mov_b32 s39, s36
	s_mov_b32 s37, s36
	v_mov_b64_e32 v[146:147], s[38:39]
	v_mov_b64_e32 v[144:145], s[36:37]
	v_cvt_pk_bf16_f32 v148, v40, v41
	v_cvt_pk_bf16_f32 v149, v42, v43
	v_cvt_pk_bf16_f32 v150, v36, v37
	v_cvt_pk_bf16_f32 v151, v38, v39
	v_mov_b32_e32 v34, 0
	v_mov_b32_e32 v35, 0
	v_mov_b32_e32 v36, 0
	v_mov_b32_e32 v37, 0
	v_dot2c_f32_bf16_e32 v34, v118, v144
	v_dot2c_f32_bf16_e32 v35, v119, v144
	v_dot2c_f32_bf16_e32 v36, v120, v144
	v_dot2c_f32_bf16_e32 v37, v121, v144
	s_waitcnt lgkmcnt(6)
	v_mfma_f32_32x32x16_bf16 v[2:17], v[114:117], v[118:121], v[2:17]
	v_add_u32_e32 v0, 0x14800, v126
	ds_read_b64_tr_b16 v[114:115], v0
	v_add_u32_e32 v0, 0x14a00, v126
	ds_read_b64_tr_b16 v[116:117], v0
	v_sub_f32_e32 v0, v51, v143
	v_sub_f32_e32 v51, v129, v143
	v_sub_f32_e32 v128, v134, v143
	v_sub_f32_e32 v129, v135, v143
	v_exp_f32_e32 v0, v0
	v_exp_f32_e32 v51, v51
	v_exp_f32_e32 v128, v128
	v_exp_f32_e32 v129, v129
	s_waitcnt lgkmcnt(6)
	v_mfma_f32_32x32x16_bf16 v[18:33], v[88:91], v[118:121], v[18:33]
	v_add_u32_e32 v88, 0x15800, v126
	v_add_u32_e32 v90, 0x15a00, v126
	v_sub_f32_e32 v118, v130, v143
	ds_read_b64_tr_b16 v[88:89], v88
	ds_read_b64_tr_b16 v[90:91], v90
	v_exp_f32_e32 v120, v118
	v_sub_f32_e32 v118, v131, v143
	v_exp_f32_e32 v121, v118
	v_sub_f32_e32 v118, v136, v143
	v_exp_f32_e32 v130, v118
	v_sub_f32_e32 v118, v137, v143
	v_exp_f32_e32 v131, v118
	v_dot2c_f32_bf16_e32 v34, v148, v144
	v_dot2c_f32_bf16_e32 v35, v149, v144
	v_dot2c_f32_bf16_e32 v36, v150, v144
	v_dot2c_f32_bf16_e32 v37, v151, v144
	v_cvt_pk_bf16_f32 v118, v0, v51
	v_cvt_pk_bf16_f32 v119, v128, v129
	v_cvt_pk_bf16_f32 v120, v120, v121
	v_cvt_pk_bf16_f32 v121, v130, v131
	s_waitcnt lgkmcnt(6)
	v_mfma_f32_32x32x16_bf16 v[2:17], v[92:95], v[148:151], v[2:17]
	v_add_u32_e32 v0, 0x14c00, v126
	ds_read_b64_tr_b16 v[92:93], v0
	v_add_u32_e32 v0, 0x14e00, v126
	ds_read_b64_tr_b16 v[94:95], v0
	v_sub_f32_e32 v128, v140, v143
	v_sub_f32_e32 v0, v132, v143
	v_sub_f32_e32 v51, v133, v143
	v_exp_f32_e32 v129, v128
	v_sub_f32_e32 v128, v141, v143
	v_exp_f32_e32 v0, v0
	v_exp_f32_e32 v51, v51
	v_exp_f32_e32 v130, v128
	s_waitcnt lgkmcnt(6)
	v_mfma_f32_32x32x16_bf16 v[18:33], v[84:87], v[148:151], v[18:33]
	v_add_u32_e32 v84, 0x15c00, v126
	v_add_u32_e32 v86, 0x15e00, v126
	ds_read_b64_tr_b16 v[84:85], v84
	ds_read_b64_tr_b16 v[86:87], v86
	v_sub_f32_e32 v128, v139, v143
	v_sub_f32_e32 v126, v138, v143
	v_exp_f32_e32 v131, v128
	v_sub_f32_e32 v128, v142, v143
	v_sub_f32_e32 v97, v97, v143
	v_exp_f32_e32 v126, v126
	v_exp_f32_e32 v132, v128
	v_exp_f32_e32 v97, v97
	v_dot2c_f32_bf16_e32 v34, v118, v144
	v_dot2c_f32_bf16_e32 v35, v119, v144
	v_dot2c_f32_bf16_e32 v36, v120, v144
	v_dot2c_f32_bf16_e32 v37, v121, v144
	v_cvt_pk_bf16_f32 v128, v0, v51
	v_cvt_pk_bf16_f32 v129, v129, v130
	v_cvt_pk_bf16_f32 v130, v126, v131
	v_cvt_pk_bf16_f32 v131, v132, v97
	s_waitcnt lgkmcnt(6)
	v_mfma_f32_32x32x16_bf16 v[2:17], v[114:117], v[118:121], v[2:17]
	s_waitcnt lgkmcnt(4)
	v_mfma_f32_32x32x16_bf16 v[18:33], v[88:91], v[118:121], v[18:33]
	v_dot2c_f32_bf16_e32 v34, v128, v144
	v_dot2c_f32_bf16_e32 v35, v129, v144
	v_dot2c_f32_bf16_e32 v36, v130, v144
	v_dot2c_f32_bf16_e32 v37, v131, v144
	s_nop 2
	v_add_f32_e32 v34, v34, v35
	v_add_f32_e32 v36, v36, v37
	v_add_f32_e32 v34, v34, v36
	v_mov_b32_e32 v35, v34
	s_nop 1
	v_permlane32_swap_b32_e32 v34, v35
	v_add_f32_e32 v34, v34, v35
	s_waitcnt lgkmcnt(2)
	v_mfma_f32_32x32x16_bf16 v[2:17], v[92:95], v[128:131], v[2:17]
	s_waitcnt lgkmcnt(0)
	v_mfma_f32_32x32x16_bf16 v[18:33], v[84:87], v[128:131], v[18:33]
	s_nop 7
	v_fmac_f32_e32 v34, v50, v96
	v_add_u32_e32 v124, 0x4000, v124
	s_cmp_lt_u32 s12, s22
	v_add_u32_e32 v125, 0x200, v125
	s_cbranch_scc0 .LBB0_820

.LBB0_835:
	v_cvt_pk_bf16_f32 v142, v127, v142
	v_cvt_pk_bf16_f32 v143, v143, v144
	v_cvt_pk_bf16_f32 v144, v56, v57
	v_cvt_pk_bf16_f32 v145, v58, v59
	s_mov_b32 s38, s36
	s_mov_b32 s39, s36
	s_mov_b32 s37, s36
	v_mov_b64_e32 v[148:149], s[38:39]
	v_mov_b64_e32 v[146:147], s[36:37]
	v_cvt_pk_bf16_f32 v150, v52, v53
	v_cvt_pk_bf16_f32 v151, v54, v55
	v_cvt_pk_bf16_f32 v153, v50, v51
	v_mov_b32_e32 v50, 0
	v_mov_b32_e32 v51, 0
	v_mov_b32_e32 v52, 0
	v_mov_b32_e32 v53, 0
	v_dot2c_f32_bf16_e32 v50, v142, v146
	v_dot2c_f32_bf16_e32 v51, v143, v146
	v_dot2c_f32_bf16_e32 v52, v144, v146
	v_dot2c_f32_bf16_e32 v53, v145, v146
	v_cvt_pk_bf16_f32 v152, v48, v49
	s_waitcnt lgkmcnt(6)
	v_mfma_f32_32x32x16_bf16 v[2:17], v[114:117], v[142:145], v[2:17]
	v_add_u32_e32 v48, 0x12800, v126
	ds_read_b64_tr_b16 v[114:115], v48
	v_add_u32_e32 v48, 0x12a00, v126
	ds_read_b64_tr_b16 v[116:117], v48
	v_sub_f32_e32 v48, v118, v141
	v_sub_f32_e32 v118, v131, v141
	v_sub_f32_e32 v49, v119, v141
	v_exp_f32_e32 v119, v118
	v_sub_f32_e32 v118, v132, v141
	v_exp_f32_e32 v48, v48
	v_exp_f32_e32 v49, v49
	v_exp_f32_e32 v127, v118
	s_waitcnt lgkmcnt(6)
	v_mfma_f32_32x32x16_bf16 v[18:33], v[44:47], v[142:145], v[18:33]
	v_add_u32_e32 v44, 0x13800, v126
	v_add_u32_e32 v46, 0x13a00, v126
	ds_read_b64_tr_b16 v[44:45], v44
	ds_read_b64_tr_b16 v[46:47], v46
	v_sub_f32_e32 v118, v120, v141
	v_exp_f32_e32 v120, v118
	v_sub_f32_e32 v118, v121, v141
	v_exp_f32_e32 v121, v118
	v_sub_f32_e32 v118, v133, v141
	v_exp_f32_e32 v131, v118
	v_sub_f32_e32 v118, v134, v141
	v_exp_f32_e32 v132, v118
	v_dot2c_f32_bf16_e32 v50, v150, v146
	v_dot2c_f32_bf16_e32 v51, v151, v146
	v_dot2c_f32_bf16_e32 v52, v152, v146
	v_dot2c_f32_bf16_e32 v53, v153, v146
	v_cvt_pk_bf16_f32 v118, v48, v49
	v_cvt_pk_bf16_f32 v119, v119, v127
	v_cvt_pk_bf16_f32 v120, v120, v121
	v_cvt_pk_bf16_f32 v121, v131, v132
	s_waitcnt lgkmcnt(6)
	v_mfma_f32_32x32x16_bf16 v[2:17], v[40:43], v[150:153], v[2:17]
	v_add_u32_e32 v40, 0x12c00, v126
	v_add_u32_e32 v42, 0x12e00, v126
	ds_read_b64_tr_b16 v[40:41], v40
	ds_read_b64_tr_b16 v[42:43], v42
	v_sub_f32_e32 v48, v129, v141
	v_sub_f32_e32 v49, v130, v141
	v_sub_f32_e32 v127, v137, v141
	v_sub_f32_e32 v129, v138, v141
	v_exp_f32_e32 v48, v48
	v_exp_f32_e32 v49, v49
	v_exp_f32_e32 v127, v127
	v_exp_f32_e32 v129, v129
	s_waitcnt lgkmcnt(6)
	v_mfma_f32_32x32x16_bf16 v[18:33], v[36:39], v[150:153], v[18:33]
	v_add_u32_e32 v36, 0x13c00, v126
	v_add_u32_e32 v38, 0x13e00, v126
	ds_read_b64_tr_b16 v[36:37], v36
	ds_read_b64_tr_b16 v[38:39], v38
	v_sub_f32_e32 v130, v135, v141
	v_exp_f32_e32 v132, v130
	v_sub_f32_e32 v130, v136, v141
	v_exp_f32_e32 v133, v130
	v_sub_f32_e32 v130, v139, v141
	v_exp_f32_e32 v134, v130
	v_sub_f32_e32 v130, v140, v141
	v_exp_f32_e32 v135, v130
	v_dot2c_f32_bf16_e32 v50, v118, v146
	v_dot2c_f32_bf16_e32 v51, v119, v146
	v_dot2c_f32_bf16_e32 v52, v120, v146
	v_dot2c_f32_bf16_e32 v53, v121, v146
	v_cvt_pk_bf16_f32 v130, v48, v49
	v_cvt_pk_bf16_f32 v131, v127, v129
	v_cvt_pk_bf16_f32 v132, v132, v133
	v_cvt_pk_bf16_f32 v133, v134, v135
	s_waitcnt lgkmcnt(6)
	v_mfma_f32_32x32x16_bf16 v[2:17], v[114:117], v[118:121], v[2:17]
	s_waitcnt lgkmcnt(4)
	v_mfma_f32_32x32x16_bf16 v[18:33], v[44:47], v[118:121], v[18:33]
	v_dot2c_f32_bf16_e32 v50, v130, v146
	v_dot2c_f32_bf16_e32 v51, v131, v146
	v_dot2c_f32_bf16_e32 v52, v132, v146
	v_dot2c_f32_bf16_e32 v53, v133, v146
	s_nop 2
	v_add_f32_e32 v50, v50, v51
	v_add_f32_e32 v52, v52, v53
	v_add_f32_e32 v50, v50, v52
	v_mov_b32_e32 v51, v50
	s_nop 1
	v_permlane32_swap_b32_e32 v50, v51
	v_add_f32_e32 v50, v50, v51
	s_waitcnt lgkmcnt(2)
	v_mfma_f32_32x32x16_bf16 v[2:17], v[40:43], v[130:133], v[2:17]
	s_waitcnt lgkmcnt(0)
	v_mfma_f32_32x32x16_bf16 v[18:33], v[36:39], v[130:133], v[18:33]
	v_add_u32_e32 v36, 0x22600, v35
	ds_read2_b32 v[36:37], v36 offset1:1
	s_waitcnt lgkmcnt(0)
	v_add_f32_e32 v48, v66, v36
	v_add_u32_e32 v36, 0x22680, v35
	ds_read2_b32 v[38:39], v36 offset1:1
	v_add_u32_e32 v36, 0x22608, v35
	v_add_f32_e32 v49, v67, v37
	ds_read2_b32 v[36:37], v36 offset1:1
	s_waitcnt lgkmcnt(1)
	v_add_f32_e32 v51, v82, v38
	v_add_f32_e32 v129, v83, v39
	s_waitcnt lgkmcnt(0)
	v_add_f32_e32 v144, v68, v36
	v_add_u32_e32 v36, 0x22688, v35
	ds_read2_b32 v[38:39], v36 offset1:1
	v_add_u32_e32 v36, 0x22620, v35
	v_add_f32_e32 v146, v69, v37
	ds_read2_b32 v[36:37], v36 offset1:1
	s_waitcnt lgkmcnt(1)
	v_add_f32_e32 v134, v84, v38
	v_add_f32_e32 v135, v85, v39
	s_waitcnt lgkmcnt(0)
	v_add_f32_e32 v145, v70, v36
	v_add_u32_e32 v36, 0x226a0, v35
	ds_read2_b32 v[38:39], v36 offset1:1
	v_add_u32_e32 v36, 0x22628, v35
	v_add_f32_e32 v147, v71, v37
	ds_read2_b32 v[36:37], v36 offset1:1
	s_waitcnt lgkmcnt(1)
	v_add_f32_e32 v130, v86, v38
	v_add_f32_e32 v131, v87, v39
	s_waitcnt lgkmcnt(0)
	v_add_f32_e32 v148, v72, v36
	v_add_u32_e32 v36, 0x226a8, v35
	ds_read2_b32 v[38:39], v36 offset1:1
	v_add_u32_e32 v36, 0x22640, v35
	v_add_f32_e32 v150, v73, v37
	ds_read2_b32 v[36:37], v36 offset1:1
	s_waitcnt lgkmcnt(1)
	v_add_f32_e32 v136, v88, v38
	v_add_f32_e32 v137, v89, v39
	s_waitcnt lgkmcnt(0)
	v_add_f32_e32 v149, v74, v36
	v_add_u32_e32 v36, 0x226c0, v35
	ds_read2_b32 v[38:39], v36 offset1:1
	v_add_u32_e32 v36, 0x22648, v35
	v_add_f32_e32 v151, v75, v37
	ds_read2_b32 v[36:37], v36 offset1:1
	s_waitcnt lgkmcnt(1)
	v_add_f32_e32 v132, v90, v38
	v_add_f32_e32 v133, v91, v39
	s_waitcnt lgkmcnt(0)
	v_add_f32_e32 v152, v76, v36
	v_add_u32_e32 v36, 0x226c8, v35
	ds_read2_b32 v[38:39], v36 offset1:1
	v_add_u32_e32 v36, 0x22660, v35
	v_add_f32_e32 v154, v77, v37
	ds_read2_b32 v[36:37], v36 offset1:1
	s_waitcnt lgkmcnt(1)
	v_add_f32_e32 v140, v92, v38
	v_add_f32_e32 v141, v93, v39
	s_waitcnt lgkmcnt(0)
	v_add_f32_e32 v153, v78, v36
	v_add_u32_e32 v36, 0x226e0, v35
	ds_read2_b32 v[38:39], v36 offset1:1
	v_add_u32_e32 v36, 0x22668, v35
	v_add_u32_e32 v35, 0x226e8, v35
	v_add_f32_e32 v155, v79, v37
	ds_read2_b32 v[36:37], v36 offset1:1
	s_waitcnt lgkmcnt(1)
	v_add_f32_e32 v138, v94, v38
	v_add_f32_e32 v139, v95, v39
	ds_read2_b32 v[38:39], v35 offset1:1
	s_waitcnt lgkmcnt(1)
	v_add_f32_e32 v156, v80, v36
	v_add_f32_e32 v157, v81, v37
	s_waitcnt lgkmcnt(0)
	v_add_f32_e32 v142, v96, v38
	v_add_f32_e32 v97, v97, v39
	s_add_i32 s12, s12, 2
	s_min_i32 s4, s12, s28
	s_sub_i32 s4, s4, s20
	s_mulk_i32 s4, 0x2400
	v_add_u32_e32 v36, s4, v123
	ds_read_b128 v[52:55], v36
	ds_read_b128 v[84:87], v36 offset:32
	ds_read_b128 v[68:71], v36 offset:4608
	ds_read_b128 v[118:121], v36 offset:64
	ds_read_b128 v[92:95], v36 offset:4640
	ds_read_b128 v[44:47], v36 offset:4672
	v_add_u32_e32 v35, 0x14000, v126
	v_max3_f32 v37, v240, v48, v49
	v_max3_f32 v38, v240, v144, v146
	s_nop 0
	v_max3_f32 v56, v37, v51, v129
	v_max3_f32 v57, v38, v134, v135
	s_nop 0
	v_max3_f32 v56, v56, v145, v147
	v_max3_f32 v57, v57, v148, v150
	ds_read_b128 v[40:43], v36 offset:96
	ds_read_b128 v[36:39], v36 offset:4704
	v_max3_f32 v72, v56, v130, v131
	v_max3_f32 v73, v57, v136, v137
	s_waitcnt lgkmcnt(7)
	v_mfma_f32_32x32x16_bf16 v[52:67], v[52:55], v[98:101], 0
	v_max3_f32 v72, v72, v149, v151
	v_max3_f32 v73, v73, v152, v154
	s_nop 0
	v_max3_f32 v96, v72, v132, v133
	v_max3_f32 v127, v73, v140, v141
	s_waitcnt lgkmcnt(5)
	v_mfma_f32_32x32x16_bf16 v[68:83], v[68:71], v[98:101], 0
	v_add_u32_e32 v88, 0x14200, v126
	v_add_u32_e32 v89, 0x15000, v126
	v_add_u32_e32 v90, 0x15200, v126
	v_mfma_f32_32x32x16_bf16 v[52:67], v[84:87], v[102:105], v[52:67]
	ds_read_b64_tr_b16 v[114:115], v35
	ds_read_b64_tr_b16 v[116:117], v88
	ds_read_b64_tr_b16 v[88:89], v89
	ds_read_b64_tr_b16 v[90:91], v90
	v_max3_f32 v35, v96, v153, v155
	v_max3_f32 v84, v127, v156, v157
	s_nop 0
	v_max3_f32 v35, v35, v138, v139
	v_max3_f32 v84, v84, v142, v97
	s_waitcnt lgkmcnt(7)
	v_mfma_f32_32x32x16_bf16 v[68:83], v[92:95], v[102:105], v[68:83]
	v_max_f32_e32 v35, v35, v84
	v_mov_b32_e32 v127, v128
	v_mov_b32_e32 v84, v35
	s_nop 1
	v_permlane32_swap_b32_e32 v35, v84
	v_max_f32_e32 v35, v35, v84
	v_add_f32_e32 v84, 0x40a00000, v128
	v_cmp_gt_f32_e32 vcc, v35, v84
	s_cbranch_vccz .LBB0_837
	v_add_f32_e32 v35, 0, v35
	v_max_f32_e32 v127, v128, v35

.LBB0_934:
	v_cvt_pk_bf16_f32 v136, v130, v131
	v_cvt_pk_bf16_f32 v137, v132, v133
	ds_read_b64_tr_b16 v[130:131], v113 offset:18432
	ds_read_b64_tr_b16 v[132:133], v113 offset:18944
	ds_read_b64_tr_b16 v[138:139], v113 offset:22528
	ds_read_b64_tr_b16 v[140:141], v113 offset:23040
	ds_read_b64_tr_b16 v[192:193], v113 offset:26624
	ds_read_b64_tr_b16 v[194:195], v113 offset:27136
	ds_read_b64_tr_b16 v[220:221], v113 offset:30720
	ds_read_b64_tr_b16 v[222:223], v113 offset:31232
	ds_read_b64_tr_b16 v[224:225], v113 offset:19456
	ds_read_b64_tr_b16 v[226:227], v113 offset:19968
	ds_read_b64_tr_b16 v[228:229], v113 offset:23552
	ds_read_b64_tr_b16 v[230:231], v113 offset:24064
	ds_read_b64_tr_b16 v[232:233], v113 offset:27648
	ds_read_b64_tr_b16 v[234:235], v113 offset:28160
	ds_read_b64_tr_b16 v[246:247], v113 offset:31744
	ds_read_b64_tr_b16 v[248:249], v113 offset:32256
	v_cvt_pk_bf16_f32 v134, v126, v127
	v_cvt_pk_bf16_f32 v135, v128, v129
	s_mov_b32 s38, s36
	s_mov_b32 s39, s36
	s_mov_b32 s37, s36
	v_mov_b64_e32 v[198:199], s[38:39]
	v_mov_b64_e32 v[196:197], s[36:37]
	v_cvt_pk_bf16_f32 v200, v118, v119
	v_cvt_pk_bf16_f32 v201, v120, v121
	v_cvt_pk_bf16_f32 v202, v114, v115
	v_cvt_pk_bf16_f32 v203, v116, v117
	v_mov_b32_e32 v114, 0
	v_mov_b32_e32 v115, 0
	v_mov_b32_e32 v116, 0
	v_mov_b32_e32 v117, 0
	v_dot2c_f32_bf16_e32 v114, v134, v196
	v_dot2c_f32_bf16_e32 v115, v135, v196
	v_dot2c_f32_bf16_e32 v116, v136, v196
	v_dot2c_f32_bf16_e32 v117, v137, v196
	s_waitcnt lgkmcnt(14)
	v_mfma_f32_32x32x16_bf16 v[64:79], v[130:133], v[134:137], v[64:79]
	ds_read_b64_tr_b16 v[130:131], v113 offset:20480
	ds_read_b64_tr_b16 v[132:133], v113 offset:20992
	s_waitcnt lgkmcnt(14)
	v_mfma_f32_32x32x16_bf16 v[48:63], v[138:141], v[134:137], v[48:63]
	ds_read_b64_tr_b16 v[138:139], v113 offset:24576
	ds_read_b64_tr_b16 v[140:141], v113 offset:25088
	s_waitcnt lgkmcnt(14)
	v_mfma_f32_32x32x16_bf16 v[32:47], v[192:195], v[134:137], v[32:47]
	ds_read_b64_tr_b16 v[192:193], v113 offset:28672
	ds_read_b64_tr_b16 v[194:195], v113 offset:29184
	v_exp_f32_e32 v142, v80
	v_exp_f32_e32 v143, v81
	v_exp_f32_e32 v219, v82
	v_exp_f32_e32 v236, v83
	s_waitcnt lgkmcnt(14)
	v_mfma_f32_32x32x16_bf16 v[16:31], v[220:223], v[134:137], v[16:31]
	ds_read_b64_tr_b16 v[80:81], v113 offset:32768
	ds_read_b64_tr_b16 v[82:83], v113 offset:33280
	v_exp_f32_e32 v134, v84
	v_exp_f32_e32 v135, v85
	v_exp_f32_e32 v136, v86
	v_exp_f32_e32 v87, v87
	v_dot2c_f32_bf16_e32 v114, v200, v196
	v_dot2c_f32_bf16_e32 v115, v201, v196
	v_dot2c_f32_bf16_e32 v116, v202, v196
	v_dot2c_f32_bf16_e32 v117, v203, v196
	v_cvt_pk_bf16_f32 v84, v142, v143
	v_cvt_pk_bf16_f32 v85, v219, v236
	v_cvt_pk_bf16_f32 v86, v134, v135
	v_cvt_pk_bf16_f32 v87, v136, v87
	s_waitcnt lgkmcnt(14)
	v_mfma_f32_32x32x16_bf16 v[64:79], v[224:227], v[200:203], v[64:79]
	ds_read_b64_tr_b16 v[134:135], v113 offset:21504
	ds_read_b64_tr_b16 v[136:137], v113 offset:22016
	s_waitcnt lgkmcnt(14)
	v_mfma_f32_32x32x16_bf16 v[48:63], v[228:231], v[200:203], v[48:63]
	ds_read_b64_tr_b16 v[220:221], v113 offset:25600
	ds_read_b64_tr_b16 v[222:223], v113 offset:26112
	s_waitcnt lgkmcnt(14)
	v_mfma_f32_32x32x16_bf16 v[32:47], v[232:235], v[200:203], v[32:47]
	ds_read_b64_tr_b16 v[224:225], v113 offset:29696
	ds_read_b64_tr_b16 v[226:227], v113 offset:30208
	v_exp_f32_e32 v142, v88
	v_exp_f32_e32 v143, v89
	v_exp_f32_e32 v219, v90
	v_exp_f32_e32 v228, v91
	s_waitcnt lgkmcnt(14)
	v_mfma_f32_32x32x16_bf16 v[16:31], v[246:249], v[200:203], v[16:31]
	ds_read_b64_tr_b16 v[88:89], v113 offset:33792
	ds_read_b64_tr_b16 v[90:91], v113 offset:34304
	v_exp_f32_e32 v200, v92
	v_exp_f32_e32 v201, v93
	v_exp_f32_e32 v202, v94
	v_exp_f32_e32 v95, v95
	v_dot2c_f32_bf16_e32 v114, v84, v196
	v_dot2c_f32_bf16_e32 v115, v85, v196
	v_dot2c_f32_bf16_e32 v116, v86, v196
	v_dot2c_f32_bf16_e32 v117, v87, v196
	v_cvt_pk_bf16_f32 v92, v142, v143
	v_cvt_pk_bf16_f32 v93, v219, v228
	v_cvt_pk_bf16_f32 v94, v200, v201
	v_cvt_pk_bf16_f32 v95, v202, v95
	s_waitcnt lgkmcnt(14)
	v_mfma_f32_32x32x16_bf16 v[64:79], v[130:133], v[84:87], v[64:79]
	s_waitcnt lgkmcnt(12)
	v_mfma_f32_32x32x16_bf16 v[48:63], v[138:141], v[84:87], v[48:63]
	s_waitcnt lgkmcnt(10)
	v_mfma_f32_32x32x16_bf16 v[32:47], v[192:195], v[84:87], v[32:47]
	s_waitcnt lgkmcnt(8)
	v_mfma_f32_32x32x16_bf16 v[16:31], v[80:83], v[84:87], v[16:31]
	v_dot2c_f32_bf16_e32 v114, v92, v196
	v_dot2c_f32_bf16_e32 v115, v93, v196
	v_dot2c_f32_bf16_e32 v116, v94, v196
	v_dot2c_f32_bf16_e32 v117, v95, v196
	s_nop 2
	v_add_f32_e32 v114, v114, v115
	v_add_f32_e32 v116, v116, v117
	v_add_f32_e32 v114, v114, v116
	v_mov_b32_e32 v115, v114
	s_nop 1
	v_permlane32_swap_b32_e32 v114, v115
	v_add_f32_e32 v114, v114, v115
	s_and_saveexec_b64 s[0:1], s[44:45]
	s_cbranch_execz .LBB0_936
	s_waitcnt vmcnt(2)
	ds_write_b128 v207, v[2:5]

.LBB0_951:
	ds_read_b64_tr_b16 v[192:193], v113 offset:34816
	ds_read_b64_tr_b16 v[194:195], v113 offset:35328
	ds_read_b64_tr_b16 v[196:197], v113 offset:38912
	ds_read_b64_tr_b16 v[198:199], v113 offset:39424
	ds_read_b64_tr_b16 v[200:201], v113 offset:43008
	ds_read_b64_tr_b16 v[202:203], v113 offset:43520
	ds_read_b64_tr_b16 v[220:221], v113 offset:47104
	ds_read_b64_tr_b16 v[222:223], v113 offset:47616
	ds_read_b64_tr_b16 v[224:225], v113 offset:35840
	ds_read_b64_tr_b16 v[226:227], v113 offset:36352
	ds_read_b64_tr_b16 v[228:229], v113 offset:39936
	ds_read_b64_tr_b16 v[230:231], v113 offset:40448
	ds_read_b64_tr_b16 v[232:233], v113 offset:44032
	ds_read_b64_tr_b16 v[234:235], v113 offset:44544
	ds_read_b64_tr_b16 v[246:247], v113 offset:48128
	ds_read_b64_tr_b16 v[248:249], v113 offset:48640
	v_cvt_pk_bf16_f32 v124, v144, v145
	v_cvt_pk_bf16_f32 v125, v146, v147
	v_cvt_pk_bf16_f32 v126, v148, v149
	v_cvt_pk_bf16_f32 v127, v150, v151
	s_mov_b32 s38, s36
	s_mov_b32 s39, s36
	s_mov_b32 s37, s36
	v_mov_b64_e32 v[244:245], s[38:39]
	v_mov_b64_e32 v[242:243], s[36:37]
	v_cvt_pk_bf16_f32 v120, v120, v121
	v_cvt_pk_bf16_f32 v121, v122, v123
	v_mov_b32_e32 v144, 0
	v_mov_b32_e32 v145, 0
	v_mov_b32_e32 v146, 0
	v_mov_b32_e32 v147, 0
	v_dot2c_f32_bf16_e32 v144, v124, v242
	v_dot2c_f32_bf16_e32 v145, v125, v242
	v_dot2c_f32_bf16_e32 v146, v126, v242
	v_dot2c_f32_bf16_e32 v147, v127, v242
	v_cvt_pk_bf16_f32 v122, v116, v117
	v_cvt_pk_bf16_f32 v123, v118, v119
	s_waitcnt lgkmcnt(14)
	v_mfma_f32_32x32x16_bf16 v[64:79], v[192:195], v[124:127], v[64:79]
	ds_read_b64_tr_b16 v[116:117], v113 offset:36864
	ds_read_b64_tr_b16 v[118:119], v113 offset:37376
	s_waitcnt lgkmcnt(14)
	v_mfma_f32_32x32x16_bf16 v[48:63], v[196:199], v[124:127], v[48:63]
	ds_read_b64_tr_b16 v[192:193], v113 offset:40960
	ds_read_b64_tr_b16 v[194:195], v113 offset:41472
	s_waitcnt lgkmcnt(14)
	v_mfma_f32_32x32x16_bf16 v[32:47], v[200:203], v[124:127], v[32:47]
	ds_read_b64_tr_b16 v[196:197], v113 offset:45056
	ds_read_b64_tr_b16 v[198:199], v113 offset:45568
	v_exp_f32_e32 v200, v96
	v_exp_f32_e32 v201, v97
	v_exp_f32_e32 v202, v98
	v_exp_f32_e32 v203, v99
	s_waitcnt lgkmcnt(14)
	v_mfma_f32_32x32x16_bf16 v[16:31], v[220:223], v[124:127], v[16:31]
	ds_read_b64_tr_b16 v[96:97], v113 offset:49152
	ds_read_b64_tr_b16 v[98:99], v113 offset:49664
	v_exp_f32_e32 v124, v100
	v_exp_f32_e32 v125, v101
	v_exp_f32_e32 v126, v102
	v_exp_f32_e32 v103, v103
	v_dot2c_f32_bf16_e32 v144, v120, v242
	v_dot2c_f32_bf16_e32 v145, v121, v242
	v_dot2c_f32_bf16_e32 v146, v122, v242
	v_dot2c_f32_bf16_e32 v147, v123, v242
	v_cvt_pk_bf16_f32 v100, v200, v201
	v_cvt_pk_bf16_f32 v101, v202, v203
	v_cvt_pk_bf16_f32 v102, v124, v125
	v_cvt_pk_bf16_f32 v103, v126, v103
	s_waitcnt lgkmcnt(14)
	v_mfma_f32_32x32x16_bf16 v[64:79], v[224:227], v[120:123], v[64:79]
	ds_read_b64_tr_b16 v[124:125], v113 offset:37888
	ds_read_b64_tr_b16 v[126:127], v113 offset:38400
	s_waitcnt lgkmcnt(14)
	v_mfma_f32_32x32x16_bf16 v[48:63], v[228:231], v[120:123], v[48:63]
	ds_read_b64_tr_b16 v[200:201], v113 offset:41984
	ds_read_b64_tr_b16 v[202:203], v113 offset:42496
	s_waitcnt lgkmcnt(14)
	v_mfma_f32_32x32x16_bf16 v[32:47], v[232:235], v[120:123], v[32:47]
	ds_read_b64_tr_b16 v[220:221], v113 offset:46080
	ds_read_b64_tr_b16 v[222:223], v113 offset:46592
	v_exp_f32_e32 v219, v104
	v_exp_f32_e32 v224, v105
	v_exp_f32_e32 v225, v106
	v_exp_f32_e32 v226, v107
	s_waitcnt lgkmcnt(14)
	v_mfma_f32_32x32x16_bf16 v[16:31], v[246:249], v[120:123], v[16:31]
	ds_read_b64_tr_b16 v[104:105], v113 offset:50176
	ds_read_b64_tr_b16 v[106:107], v113 offset:50688
	v_exp_f32_e32 v120, v108
	v_exp_f32_e32 v121, v109
	v_exp_f32_e32 v122, v110
	v_exp_f32_e32 v111, v111
	v_dot2c_f32_bf16_e32 v144, v100, v242
	v_dot2c_f32_bf16_e32 v145, v101, v242
	v_dot2c_f32_bf16_e32 v146, v102, v242
	v_dot2c_f32_bf16_e32 v147, v103, v242
	v_cvt_pk_bf16_f32 v108, v219, v224
	v_cvt_pk_bf16_f32 v109, v225, v226
	v_cvt_pk_bf16_f32 v110, v120, v121
	v_cvt_pk_bf16_f32 v111, v122, v111
	s_waitcnt lgkmcnt(14)
	v_mfma_f32_32x32x16_bf16 v[64:79], v[116:119], v[100:103], v[64:79]
	s_waitcnt lgkmcnt(12)
	v_mfma_f32_32x32x16_bf16 v[48:63], v[192:195], v[100:103], v[48:63]
	s_waitcnt lgkmcnt(10)
	v_mfma_f32_32x32x16_bf16 v[32:47], v[196:199], v[100:103], v[32:47]
	s_waitcnt lgkmcnt(8)
	v_mfma_f32_32x32x16_bf16 v[16:31], v[96:99], v[100:103], v[16:31]
	v_dot2c_f32_bf16_e32 v144, v108, v242
	v_dot2c_f32_bf16_e32 v145, v109, v242
	v_dot2c_f32_bf16_e32 v146, v110, v242
	v_dot2c_f32_bf16_e32 v147, v111, v242
	s_nop 2
	v_add_f32_e32 v144, v144, v145
	v_add_f32_e32 v146, v146, v147
	v_add_f32_e32 v144, v144, v146
	v_mov_b32_e32 v145, v144
	s_nop 1
	v_permlane32_swap_b32_e32 v144, v145
	v_add_f32_e32 v144, v144, v145
	s_and_saveexec_b64 s[0:1], s[44:45]
	s_cbranch_execz .LBB0_953
	s_waitcnt vmcnt(2)
	ds_write_b128 v207, v[2:5] offset:9216

.LBB0_980:
	v_cvt_pk_bf16_f32 v136, v130, v131
	v_cvt_pk_bf16_f32 v137, v132, v133
	ds_read_b64_tr_b16 v[130:131], v113 offset:18432
	ds_read_b64_tr_b16 v[132:133], v113 offset:18944
	ds_read_b64_tr_b16 v[138:139], v113 offset:22528
	ds_read_b64_tr_b16 v[140:141], v113 offset:23040
	ds_read_b64_tr_b16 v[192:193], v113 offset:26624
	ds_read_b64_tr_b16 v[194:195], v113 offset:27136
	ds_read_b64_tr_b16 v[196:197], v113 offset:30720
	ds_read_b64_tr_b16 v[198:199], v113 offset:31232
	ds_read_b64_tr_b16 v[200:201], v113 offset:19456
	ds_read_b64_tr_b16 v[202:203], v113 offset:19968
	ds_read_b64_tr_b16 v[220:221], v113 offset:23552
	ds_read_b64_tr_b16 v[222:223], v113 offset:24064
	ds_read_b64_tr_b16 v[224:225], v113 offset:27648
	ds_read_b64_tr_b16 v[226:227], v113 offset:28160
	ds_read_b64_tr_b16 v[228:229], v113 offset:31744
	ds_read_b64_tr_b16 v[230:231], v113 offset:32256
	v_cvt_pk_bf16_f32 v134, v126, v127
	v_cvt_pk_bf16_f32 v135, v128, v129
	s_mov_b32 s38, s36
	s_mov_b32 s39, s36
	s_mov_b32 s37, s36
	v_mov_b64_e32 v[234:235], s[38:39]
	v_mov_b64_e32 v[232:233], s[36:37]
	v_cvt_pk_bf16_f32 v242, v118, v119
	v_cvt_pk_bf16_f32 v243, v120, v121
	v_cvt_pk_bf16_f32 v244, v114, v115
	v_cvt_pk_bf16_f32 v245, v116, v117
	v_mov_b32_e32 v114, 0
	v_mov_b32_e32 v115, 0
	v_mov_b32_e32 v116, 0
	v_mov_b32_e32 v117, 0
	v_dot2c_f32_bf16_e32 v114, v134, v232
	v_dot2c_f32_bf16_e32 v115, v135, v232
	v_dot2c_f32_bf16_e32 v116, v136, v232
	v_dot2c_f32_bf16_e32 v117, v137, v232
	s_waitcnt lgkmcnt(14)
	v_mfma_f32_32x32x16_bf16 v[64:79], v[130:133], v[134:137], v[64:79]
	ds_read_b64_tr_b16 v[130:131], v113 offset:20480
	ds_read_b64_tr_b16 v[132:133], v113 offset:20992
	s_waitcnt lgkmcnt(14)
	v_mfma_f32_32x32x16_bf16 v[48:63], v[138:141], v[134:137], v[48:63]
	ds_read_b64_tr_b16 v[138:139], v113 offset:24576
	ds_read_b64_tr_b16 v[140:141], v113 offset:25088
	s_waitcnt lgkmcnt(14)
	v_mfma_f32_32x32x16_bf16 v[32:47], v[192:195], v[134:137], v[32:47]
	ds_read_b64_tr_b16 v[192:193], v113 offset:28672
	ds_read_b64_tr_b16 v[194:195], v113 offset:29184
	v_exp_f32_e32 v142, v80
	v_exp_f32_e32 v143, v81
	v_exp_f32_e32 v219, v82
	v_exp_f32_e32 v236, v83
	s_waitcnt lgkmcnt(14)
	v_mfma_f32_32x32x16_bf16 v[16:31], v[196:199], v[134:137], v[16:31]
	ds_read_b64_tr_b16 v[80:81], v113 offset:32768
	ds_read_b64_tr_b16 v[82:83], v113 offset:33280
	v_exp_f32_e32 v134, v84
	v_exp_f32_e32 v135, v85
	v_exp_f32_e32 v136, v86
	v_exp_f32_e32 v87, v87
	v_dot2c_f32_bf16_e32 v114, v242, v232
	v_dot2c_f32_bf16_e32 v115, v243, v232
	v_dot2c_f32_bf16_e32 v116, v244, v232
	v_dot2c_f32_bf16_e32 v117, v245, v232
	v_cvt_pk_bf16_f32 v84, v142, v143
	v_cvt_pk_bf16_f32 v85, v219, v236
	v_cvt_pk_bf16_f32 v86, v134, v135
	v_cvt_pk_bf16_f32 v87, v136, v87
	s_waitcnt lgkmcnt(14)
	v_mfma_f32_32x32x16_bf16 v[64:79], v[200:203], v[242:245], v[64:79]
	ds_read_b64_tr_b16 v[134:135], v113 offset:21504
	ds_read_b64_tr_b16 v[136:137], v113 offset:22016
	s_waitcnt lgkmcnt(14)
	v_mfma_f32_32x32x16_bf16 v[48:63], v[220:223], v[242:245], v[48:63]
	ds_read_b64_tr_b16 v[196:197], v113 offset:25600
	ds_read_b64_tr_b16 v[198:199], v113 offset:26112
	s_waitcnt lgkmcnt(14)
	v_mfma_f32_32x32x16_bf16 v[32:47], v[224:227], v[242:245], v[32:47]
	ds_read_b64_tr_b16 v[200:201], v113 offset:29696
	ds_read_b64_tr_b16 v[202:203], v113 offset:30208
	v_exp_f32_e32 v142, v88
	v_exp_f32_e32 v143, v89
	v_exp_f32_e32 v219, v90
	v_exp_f32_e32 v220, v91
	s_waitcnt lgkmcnt(14)
	v_mfma_f32_32x32x16_bf16 v[16:31], v[228:231], v[242:245], v[16:31]
	ds_read_b64_tr_b16 v[88:89], v113 offset:33792
	ds_read_b64_tr_b16 v[90:91], v113 offset:34304
	v_exp_f32_e32 v221, v92
	v_exp_f32_e32 v222, v93
	v_exp_f32_e32 v223, v94
	v_exp_f32_e32 v95, v95
	v_dot2c_f32_bf16_e32 v114, v84, v232
	v_dot2c_f32_bf16_e32 v115, v85, v232
	v_dot2c_f32_bf16_e32 v116, v86, v232
	v_dot2c_f32_bf16_e32 v117, v87, v232
	v_cvt_pk_bf16_f32 v92, v142, v143
	v_cvt_pk_bf16_f32 v93, v219, v220
	v_cvt_pk_bf16_f32 v94, v221, v222
	v_cvt_pk_bf16_f32 v95, v223, v95
	s_waitcnt lgkmcnt(14)
	v_mfma_f32_32x32x16_bf16 v[64:79], v[130:133], v[84:87], v[64:79]
	s_waitcnt lgkmcnt(12)
	v_mfma_f32_32x32x16_bf16 v[48:63], v[138:141], v[84:87], v[48:63]
	s_waitcnt lgkmcnt(10)
	v_mfma_f32_32x32x16_bf16 v[32:47], v[192:195], v[84:87], v[32:47]
	s_waitcnt lgkmcnt(8)
	v_mfma_f32_32x32x16_bf16 v[16:31], v[80:83], v[84:87], v[16:31]
	v_dot2c_f32_bf16_e32 v114, v92, v232
	v_dot2c_f32_bf16_e32 v115, v93, v232
	v_dot2c_f32_bf16_e32 v116, v94, v232
	v_dot2c_f32_bf16_e32 v117, v95, v232
	s_nop 2
	v_add_f32_e32 v114, v114, v115
	v_add_f32_e32 v116, v116, v117
	v_add_f32_e32 v114, v114, v116
	v_mov_b32_e32 v115, v114
	s_nop 1
	v_permlane32_swap_b32_e32 v114, v115
	v_add_f32_e32 v114, v114, v115
	s_and_saveexec_b64 s[0:1], s[44:45]
	s_cbranch_execz .LBB0_982
	s_waitcnt vmcnt(2)
	ds_write_b128 v207, v[2:5]

.LBB0_997:
	ds_read_b64_tr_b16 v[192:193], v113 offset:34816
	ds_read_b64_tr_b16 v[194:195], v113 offset:35328
	ds_read_b64_tr_b16 v[196:197], v113 offset:38912
	ds_read_b64_tr_b16 v[198:199], v113 offset:39424
	ds_read_b64_tr_b16 v[200:201], v113 offset:43008
	ds_read_b64_tr_b16 v[202:203], v113 offset:43520
	ds_read_b64_tr_b16 v[220:221], v113 offset:47104
	ds_read_b64_tr_b16 v[222:223], v113 offset:47616
	ds_read_b64_tr_b16 v[224:225], v113 offset:35840
	ds_read_b64_tr_b16 v[226:227], v113 offset:36352
	ds_read_b64_tr_b16 v[228:229], v113 offset:39936
	ds_read_b64_tr_b16 v[230:231], v113 offset:40448
	ds_read_b64_tr_b16 v[232:233], v113 offset:44032
	ds_read_b64_tr_b16 v[234:235], v113 offset:44544
	ds_read_b64_tr_b16 v[242:243], v113 offset:48128
	ds_read_b64_tr_b16 v[244:245], v113 offset:48640
	v_cvt_pk_bf16_f32 v124, v144, v145
	v_cvt_pk_bf16_f32 v125, v146, v147
	v_cvt_pk_bf16_f32 v126, v148, v149
	v_cvt_pk_bf16_f32 v127, v150, v151
	s_mov_b32 s38, s36
	s_mov_b32 s39, s36
	s_mov_b32 s37, s36
	v_mov_b64_e32 v[248:249], s[38:39]
	v_mov_b64_e32 v[246:247], s[36:37]
	v_cvt_pk_bf16_f32 v120, v120, v121
	v_cvt_pk_bf16_f32 v121, v122, v123
	v_mov_b32_e32 v144, 0
	v_mov_b32_e32 v145, 0
	v_mov_b32_e32 v146, 0
	v_mov_b32_e32 v147, 0
	v_dot2c_f32_bf16_e32 v144, v124, v246
	v_dot2c_f32_bf16_e32 v145, v125, v246
	v_dot2c_f32_bf16_e32 v146, v126, v246
	v_dot2c_f32_bf16_e32 v147, v127, v246
	v_cvt_pk_bf16_f32 v122, v116, v117
	v_cvt_pk_bf16_f32 v123, v118, v119
	s_waitcnt lgkmcnt(14)
	v_mfma_f32_32x32x16_bf16 v[64:79], v[192:195], v[124:127], v[64:79]
	ds_read_b64_tr_b16 v[116:117], v113 offset:36864
	ds_read_b64_tr_b16 v[118:119], v113 offset:37376
	s_waitcnt lgkmcnt(14)
	v_mfma_f32_32x32x16_bf16 v[48:63], v[196:199], v[124:127], v[48:63]
	ds_read_b64_tr_b16 v[192:193], v113 offset:40960
	ds_read_b64_tr_b16 v[194:195], v113 offset:41472
	s_waitcnt lgkmcnt(14)
	v_mfma_f32_32x32x16_bf16 v[32:47], v[200:203], v[124:127], v[32:47]
	ds_read_b64_tr_b16 v[196:197], v113 offset:45056
	ds_read_b64_tr_b16 v[198:199], v113 offset:45568
	v_exp_f32_e32 v200, v96
	v_exp_f32_e32 v201, v97
	v_exp_f32_e32 v202, v98
	v_exp_f32_e32 v203, v99
	s_waitcnt lgkmcnt(14)
	v_mfma_f32_32x32x16_bf16 v[16:31], v[220:223], v[124:127], v[16:31]
	ds_read_b64_tr_b16 v[96:97], v113 offset:49152
	ds_read_b64_tr_b16 v[98:99], v113 offset:49664
	v_exp_f32_e32 v124, v100
	v_exp_f32_e32 v125, v101
	v_exp_f32_e32 v126, v102
	v_exp_f32_e32 v103, v103
	v_dot2c_f32_bf16_e32 v144, v120, v246
	v_dot2c_f32_bf16_e32 v145, v121, v246
	v_dot2c_f32_bf16_e32 v146, v122, v246
	v_dot2c_f32_bf16_e32 v147, v123, v246
	v_cvt_pk_bf16_f32 v100, v200, v201
	v_cvt_pk_bf16_f32 v101, v202, v203
	v_cvt_pk_bf16_f32 v102, v124, v125
	v_cvt_pk_bf16_f32 v103, v126, v103
	s_waitcnt lgkmcnt(14)
	v_mfma_f32_32x32x16_bf16 v[64:79], v[224:227], v[120:123], v[64:79]
	ds_read_b64_tr_b16 v[124:125], v113 offset:37888
	ds_read_b64_tr_b16 v[126:127], v113 offset:38400
	s_waitcnt lgkmcnt(14)
	v_mfma_f32_32x32x16_bf16 v[48:63], v[228:231], v[120:123], v[48:63]
	ds_read_b64_tr_b16 v[200:201], v113 offset:41984
	ds_read_b64_tr_b16 v[202:203], v113 offset:42496
	s_waitcnt lgkmcnt(14)
	v_mfma_f32_32x32x16_bf16 v[32:47], v[232:235], v[120:123], v[32:47]
	ds_read_b64_tr_b16 v[220:221], v113 offset:46080
	ds_read_b64_tr_b16 v[222:223], v113 offset:46592
	v_exp_f32_e32 v219, v104
	v_exp_f32_e32 v224, v105
	v_exp_f32_e32 v225, v106
	v_exp_f32_e32 v226, v107
	s_waitcnt lgkmcnt(14)
	v_mfma_f32_32x32x16_bf16 v[16:31], v[242:245], v[120:123], v[16:31]
	ds_read_b64_tr_b16 v[104:105], v113 offset:50176
	ds_read_b64_tr_b16 v[106:107], v113 offset:50688
	v_exp_f32_e32 v120, v108
	v_exp_f32_e32 v121, v109
	v_exp_f32_e32 v122, v110
	v_exp_f32_e32 v111, v111
	v_dot2c_f32_bf16_e32 v144, v100, v246
	v_dot2c_f32_bf16_e32 v145, v101, v246
	v_dot2c_f32_bf16_e32 v146, v102, v246
	v_dot2c_f32_bf16_e32 v147, v103, v246
	v_cvt_pk_bf16_f32 v108, v219, v224
	v_cvt_pk_bf16_f32 v109, v225, v226
	v_cvt_pk_bf16_f32 v110, v120, v121
	v_cvt_pk_bf16_f32 v111, v122, v111
	s_waitcnt lgkmcnt(14)
	v_mfma_f32_32x32x16_bf16 v[64:79], v[116:119], v[100:103], v[64:79]
	s_waitcnt lgkmcnt(12)
	v_mfma_f32_32x32x16_bf16 v[48:63], v[192:195], v[100:103], v[48:63]
	s_waitcnt lgkmcnt(10)
	v_mfma_f32_32x32x16_bf16 v[32:47], v[196:199], v[100:103], v[32:47]
	s_waitcnt lgkmcnt(8)
	v_mfma_f32_32x32x16_bf16 v[16:31], v[96:99], v[100:103], v[16:31]
	v_dot2c_f32_bf16_e32 v144, v108, v246
	v_dot2c_f32_bf16_e32 v145, v109, v246
	v_dot2c_f32_bf16_e32 v146, v110, v246
	v_dot2c_f32_bf16_e32 v147, v111, v246
	s_nop 2
	v_add_f32_e32 v144, v144, v145
	v_add_f32_e32 v146, v146, v147
	v_add_f32_e32 v144, v144, v146
	v_mov_b32_e32 v145, v144
	s_nop 1
	v_permlane32_swap_b32_e32 v144, v145
	v_add_f32_e32 v144, v144, v145
	s_and_saveexec_b64 s[0:1], s[44:45]
	s_cbranch_execz .LBB0_999
	s_waitcnt vmcnt(2)
	ds_write_b128 v207, v[10:13] offset:9216
